# work queue: next band item's id fetched (global atomic) during the current band item, parked in a VGPR lane; diff items keep the late fetch
# baseline (speedup 1.0000x reference)
; DI void phase_att(const Params& P, char* lds, int hb, int layer) {
;     ...
;     for (int dq = 0; dq < 8; ++dq) {
;         const int qx = (blockIdx.x + dq) & 7;
;         while (true) {
;             if (tid == 0) *slot = (int)atomicAdd(&ctr[qx], 1u);
;             __syncthreads();
;             const int qi = *slot;
.LBB0_196:
	s_add_i32 s1, s26, s33
	s_and_b32 s3, s1, 7
	s_and_b32 s0, s2, 3
	s_lshl_b32 s14, s3, 2
	s_add_u32 s56, s98, s14
	s_mulk_i32 s3, 0x180
	s_addc_u32 s57, s99, 0
	s_sub_i32 s54, s3, 64
	s_and_b32 s3, s1, 3
	s_lshl_b32 s1, s1, 11
	s_and_b32 s1, s1, 0x2000
	s_lshl_b32 s24, s3, 7
	s_mulk_i32 s1, 0x3800
	s_add_u32 s58, s34, s1
	s_addc_u32 s59, s35, 0
	s_mul_i32 s1, s3, 0x2100
	s_add_u32 s1, s46, s1
	s_addc_u32 s14, s47, 0
	s_add_u32 s20, s1, 0x20fc
	s_addc_u32 s21, s14, 0
	s_lshl_b32 s1, s3, 8
	s_add_u32 s1, s58, s1
	s_addc_u32 s15, s59, 0
	s_add_u32 s96, s1, 0x1f00
	s_addc_u32 s97, s15, 0
	s_add_u32 s14, s1, 0x2300
	s_mulk_i32 s0, 0x2100
	s_addc_u32 s15, s15, 0
	s_add_u32 s28, s46, s0
	s_addc_u32 s29, s47, 0
	v_writelane_b32 v236, -1, 62
	s_nop 3
	s_branch .LBB0_199

; DI void phase_att(const Params& P, char* lds, int hb, int layer) {
;     ...
;             if (tid == 0) *slot = (int)atomicAdd(&ctr[qx], 1u);
;             __syncthreads();
;             const int qi = *slot;
;             __syncthreads();
;             if (qi >= NQ) break;
.LBB0_199:
	s_and_saveexec_b64 s[0:1], s[36:37]
	s_cbranch_execz .LBB0_201
	v_readlane_b32 s25, v236, 62
	s_nop 3
	s_cmp_lg_u32 s25, -1
	s_cbranch_scc1 .Lwf_have
	v_mov_b64_e32 v[2:3], s[56:57]
	global_atomic_add v253, v[2:3], v176, off sc0
	s_waitcnt vmcnt(0)
	v_readfirstlane_b32 s25, v253
	s_nop 3
.Lwf_have:
	v_mov_b32_e32 v2, s53
	v_mov_b32_e32 v0, s25
	ds_write_b32 v2, v0
	s_cmpk_gt_i32 s25, 0x1bf
	s_cbranch_scc1 .Lwf_nopf
	s_cmpk_lt_i32 s25, 64
	s_cbranch_scc1 .Lwf_nopf
	s_nop 1
	v_mov_b64_e32 v[2:3], s[56:57]
	global_atomic_add v253, v[2:3], v176, off sc0
	s_branch .LBB0_201
.Lwf_nopf:
	v_writelane_b32 v236, -1, 62

; DI void band_item(const Params& P, char* lds_blk, int layer, int bp) {
;     ...
;     float* btab = (float*)(lds + 4 * 64 * GP);
;     const float* tabg = (const float*)(P.ws + WS_TABB) + (type * 12 + head) * 384;
;     for (int i = tid; i < 384; i += 256) btab[i] = tabg[i];
;     bf16x8 qf[4];
; #pragma unroll
;     for (int s = 0; s < 4; ++s) qf[s] = *(const bf16x8*)(qp + (size_t)(32 * w + r) * rs + 16 * s + 8 * h);
;     float m = -1e30f, l = 0.f;
;     if (type == 0) { m = P.sinks[layer * 12 + head] * LOG2E; l = (h == 0) ? 1.f : 0.f; }
;     f32x16 O[2];
; #pragma unroll
;     for (int dt = 0; dt < 2; ++dt)
; #pragma unroll
;         for (int i = 0; i < 16; ++i) O[dt][i] = 0.f;
;     const int maxd = type == 0 ? 127 : 128;
;     const int qpos = 128 + 32 * w + r;
;     const int kt0 = (nb == 0 ? 2 : 0);
;     u32x4 rk[2], rv[2];
;     const int srow = tid >> 3, sch = tid & 7;
;     auto gload = [&](int kt) {
; #pragma unroll
;         for (int j = 0; j < 2; ++j) {
;             const ptrdiff_t ro = ((ptrdiff_t)(64 * kt + srow + 32 * j) - 128) * (ptrdiff_t)rs + sch * 8;
;             rk[j] = *(const u32x4*)(kp + ro); rv[j] = *(const u32x4*)(vp + ro);
;         }
;     };
;     auto lstore = [&](int b) {
;         char* sK = lds + b * (2 * 64 * GP); char* sV = sK + 64 * GP;
; #pragma unroll
;         for (int j = 0; j < 2; ++j) { *(u32x4*)(sK + (srow + 32 * j) * GP + sch * 16) = rk[j]; *(u32x4*)(sV + (srow + 32 * j) * GP + sch * 16) = rv[j]; }
;     };
;     gload(kt0); lstore(0);
; DI void phase_att(const Params& P, char* lds, int hb, int layer) {
;     ...
;             if (qi >= NQ) break;
;             if (qi < 64) diff_item(P, lds, layer, qx, 63 - qi, tab_head);
;             else band_item(P, lds, layer, qx * 384 + (qi - 64));
.LBB0_212:
	s_cmp_eq_u32 s64, 0
	s_cselect_b32 s1, 2, 1
	s_cselect_b32 s100, 0, 1
	v_lshrrev_b32_sdwa v0, v191, v10 dst_sel:DWORD dst_unused:UNUSED_PAD src0_sel:DWORD src1_sel:BYTE_0
	s_lshl_b32 s64, s1, 6
	v_or_b32_e32 v15, s64, v0
	v_and_b32_e32 v113, 7, v10
	v_add_u32_e32 v3, 0xffffff80, v15
	v_mul_hi_i32_i24_e32 v13, s72, v3
	v_mul_i32_i24_e32 v12, s72, v3
	v_lshlrev_b32_e32 v110, 3, v113
	s_lshl_b32 s16, s72, 5
	v_ashrrev_i32_e32 v5, 31, v4
	v_or_b32_e32 v20, v12, v110
	v_mov_b32_e32 v21, v13
	v_lshl_add_u64 v[12:13], v[12:13], 0, s[16:17]
	v_ashrrev_i32_e32 v7, 31, v6
	v_lshlrev_b64 v[16:17], 1, v[4:5]
	v_or_b32_e32 v12, v12, v110
	v_lshl_add_u64 v[4:5], s[22:23], 0, v[16:17]
	v_lshlrev_b64 v[18:19], 1, v[6:7]
	v_lshlrev_b64 v[20:21], 1, v[20:21]
	v_lshlrev_b64 v[12:13], 1, v[12:13]
	v_lshl_add_u64 v[6:7], s[22:23], 0, v[18:19]
	v_lshl_add_u64 v[22:23], v[4:5], 0, v[20:21]
	v_lshl_add_u64 v[4:5], v[4:5], 0, v[12:13]
	v_lshl_add_u64 v[20:21], v[6:7], 0, v[20:21]
	flat_load_dwordx4 v[82:85], v[22:23]
	flat_load_dwordx4 v[86:89], v[20:21]
	v_lshl_add_u64 v[6:7], v[6:7], 0, v[12:13]
	flat_load_dwordx4 v[90:93], v[4:5]
	flat_load_dwordx4 v[94:97], v[6:7]
	v_add_u32_e32 v20, s0, v111
	v_lshlrev_b32_e32 v21, 2, v8
	v_lshrrev_b32_e32 v23, 2, v10
	v_add_u32_e32 v26, v111, v123
	s_add_i32 s0, s70, s65
	v_or_b32_e32 v22, 32, v107
	v_and_b32_e32 v24, 16, v10
	v_lshlrev_b32_e32 v25, 2, v107
	v_add_u32_e32 v128, 0x80, v20
	v_and_or_b32 v20, v23, 3, v21
	v_sub_u32_e32 v21, v26, v21
	s_add_i32 s0, s0, s71
	v_mul_u32_u24_e32 v129, 0x90, v22
	v_and_or_b32 v22, v25, 12, v24
	v_mul_u32_u24_e32 v131, 0x90, v20
	s_add_i32 s65, s1, -1
	v_subrev_u32_e32 v20, s64, v21
	s_mul_hi_u32 s1, s0, 0x3800
	s_mulk_i32 s0, 0x3800
	s_lshl_b32 s16, s72, 1
	v_lshlrev_b32_e32 v132, 1, v22
	v_lshlrev_b32_e32 v22, 2, v20
	v_subrev_u32_e32 v23, 32, v15
	v_mov_b64_e32 v[20:21], s[0:1]
	v_subrev_u32_e32 v24, 64, v15
	v_add_u32_e32 v125, 0, v14
	v_add3_u32 v134, v14, v22, s44
	v_mad_i64_i32 v[14:15], s[0:1], s16, v23, v[20:21]
	v_mad_i64_i32 v[20:21], s[0:1], s16, v24, v[20:21]
	v_mul_u32_u24_e32 v27, 0x90, v0
	v_lshlrev_b32_e32 v0, 4, v113
	v_lshl_add_u64 v[22:23], v[14:15], 0, v[18:19]
	v_lshl_add_u64 v[14:15], v[14:15], 0, v[16:17]
	v_lshl_add_u64 v[18:19], v[20:21], 0, v[18:19]
	v_lshl_add_u64 v[16:17], v[20:21], 0, v[16:17]
	v_or_b32_e32 v126, 0x9f, v111
	v_mul_u32_u24_e32 v127, 0x90, v123
	v_mov_b32_e32 v3, v2
	v_mov_b32_e32 v4, v2
	v_mov_b32_e32 v5, v2
	v_mov_b32_e32 v6, v2
	v_mov_b32_e32 v7, v2
	v_mov_b32_e32 v8, v2
	v_mov_b32_e32 v9, v2
	v_mov_b32_e32 v10, v2
	v_mov_b32_e32 v11, v2
	v_mov_b32_e32 v12, v2
	v_mov_b32_e32 v13, v2
	v_add3_u32 v130, v125, v27, v0
	s_lshl_b32 s16, s72, 7
	v_lshl_add_u64 v[114:115], s[34:35], 0, v[22:23]
	v_lshl_add_u64 v[116:117], s[34:35], 0, v[14:15]
	v_lshl_add_u64 v[118:119], s[34:35], 0, v[18:19]
	v_lshl_add_u64 v[120:121], s[34:35], 0, v[16:17]
	v_mov_b32_e32 v14, v2
	v_mov_b32_e32 v15, v2
	v_mov_b32_e32 v16, v2
	v_mov_b32_e32 v17, v2
	v_mov_b32_e32 v18, v2
	v_mov_b32_e32 v19, v2
	v_mov_b32_e32 v20, v2
	v_mov_b32_e32 v21, v2
	v_mov_b32_e32 v22, v2
	v_mov_b32_e32 v23, v2
	v_mov_b32_e32 v24, v2
	v_mov_b32_e32 v25, v2
	v_mov_b32_e32 v26, v2
	v_mov_b32_e32 v27, v2
	v_mov_b32_e32 v28, v2
	v_mov_b32_e32 v29, v2
	v_mov_b32_e32 v30, v2
	v_mov_b32_e32 v31, v2
	v_mov_b32_e32 v32, v2
	v_mov_b32_e32 v33, v2
	s_waitcnt vmcnt(0) lgkmcnt(0)
	v_readfirstlane_b32 s0, v253
	s_nop 3
	v_writelane_b32 v236, s0, 62
	ds_write_b32 v137, v136
	v_and_b32_e32 v140, 0x80, v174
	v_cmp_eq_u32_e32 vcc, 0, v140
	s_and_saveexec_b64 s[22:23], vcc
	ds_write_b32 v137, v139 offset:1024
	s_or_b64 exec, exec, s[22:23]
	s_and_b64 vcc, exec, s[40:41]
	s_cbranch_vccnz .Lbp_nosink
	v_mul_f32_e32 v133, 0x3fb8aa3b, v138
